# attention P.V per 32-key tile on bf16 MFMA with accumulators in matrix layout (weights re-staged through the logits LDS rows, output transposed back through LDS); prompt S5 B*u on f32 MFMA (v_mfma_f32
# speedup vs baseline: 1.1281x; 1.0450x over previous
; __device__ __forceinline__ void s5_item(CPar p, int l, int s, int g, float* wl) {
;     ...
;     const float lr = p->in[I_LRE][gp], li = p->in[I_LIM][gp], step = expf(p->in[I_LSTEP][l * 32 + g]);
;     float sn, cs; sincos_red((double)li * (double)step, sn, cs);
;     const float mag = expf(lr * step), ab_re = mag * cs, ab_im = mag * sn;
;     const float den = lr * lr + li * li, nr = ab_re - 1.f, f_re = (nr * lr + ab_im * li) / den, f_im = (ab_im * lr - nr * li) / den;
;     float bbr[16], bbi[16];
; #pragma unroll
;     for (int hh = 0; hh < 16; ++hh) { const float br = p->in[I_BRE][(size_t)gp * 16 + hh], bi = p->in[I_BIM][(size_t)gp * 16 + hh]; bbr[hh] = f_re * br - f_im * bi; bbi[hh] = f_re * bi + f_im * br; }
.LBB0_679:
	s_or_b64 exec, exec, s[26:27]
	v_mul_f32_e32 v2, v62, v64
	v_mul_f32_e32 v3, 0x3fb8aa3b, v2
	s_mov_b32 s6, 0x3fb8aa3b
	v_fma_f32 v61, v2, s6, -v3
	v_rndne_f32_e32 v64, v3
	v_fmac_f32_e32 v61, 0x32a5705f, v2
	v_sub_f32_e32 v3, v3, v64
	v_add_f32_e32 v3, v3, v61
	v_exp_f32_e32 v3, v3
	v_cvt_i32_f32_e32 v61, v64
	s_mov_b32 s6, 0xc2ce8ed0
	v_cmp_ngt_f32_e32 vcc, s6, v2
	s_mov_b32 s6, 0x42b17218
	v_ldexp_f32 v3, v3, v61
	v_cndmask_b32_e32 v3, 0, v3, vcc
	v_cmp_nlt_f32_e32 vcc, s6, v2
	v_mov_b32_e32 v64, v63
	v_pk_mul_f32 v[66:67], v[62:63], v[62:63]
	v_cndmask_b32_e32 v3, v206, v3, vcc
	v_mul_f32_e32 v60, v3, v60
	v_fma_f32 v61, v3, v65, -1.0
	v_mul_f32_e32 v2, v3, v65
	v_pk_mul_f32 v[64:65], v[64:65], v[60:61] op_sel:[0,1] op_sel_hi:[0,0]
	v_pk_fma_f32 v[68:69], v[62:63], v[60:61], v[64:65] neg_lo:[0,0,1] neg_hi:[0,0,1]
	v_pk_fma_f32 v[62:63], v[62:63], v[60:61], v[64:65] op_sel_hi:[0,1,1]
	v_pk_add_f32 v[64:65], v[66:67], v[66:67] op_sel:[0,1] op_sel_hi:[0,1]
	v_div_scale_f32 v3, s[6:7], v65, v65, v63
	v_rcp_f32_e32 v61, v3
	v_lshlrev_b32_e32 v1, 3, v104
	v_mov_b32_e32 v106, 0
	v_lshlrev_b32_e32 v1, 1, v1
	v_fma_f32 v62, -v3, v61, 1.0
	v_fmac_f32_e32 v61, v62, v61
	v_div_scale_f32 v62, vcc, v63, v65, v63
	v_mul_f32_e32 v66, v62, v61
	v_fma_f32 v67, -v3, v66, v62
	v_fmac_f32_e32 v66, v67, v61
	v_fma_f32 v3, -v3, v66, v62
	v_div_fmas_f32 v3, v3, v61, v66
	v_div_fixup_f32 v101, v3, v65, v63
	v_div_scale_f32 v3, s[6:7], v64, v64, v68
	v_rcp_f32_e32 v61, v3
	s_lshl_b32 s11, s9, 11
	s_mov_b32 s12, 0
	v_mov_b32_e32 v107, v106
	v_fma_f32 v62, -v3, v61, 1.0
	v_fmac_f32_e32 v61, v62, v61
	v_div_scale_f32 v62, vcc, v68, v64, v68
	v_mul_f32_e32 v63, v62, v61
	v_fma_f32 v65, -v3, v63, v62
	v_fmac_f32_e32 v63, v65, v61
	v_fma_f32 v3, -v3, v63, v62
	v_div_fmas_f32 v3, v3, v61, v63
	v_div_fixup_f32 v100, v3, v64, v68
	v_pk_mul_f32 v[66:67], v[56:57], v[100:101]
	v_pk_mul_f32 v[62:63], v[100:101], v[56:57] op_sel:[1,0] op_sel_hi:[0,1]
	v_pk_fma_f32 v[56:57], v[100:101], v[52:53], v[62:63] neg_lo:[0,0,1] neg_hi:[0,0,1]
	v_pk_fma_f32 v[62:63], v[100:101], v[52:53], v[62:63]
	v_pk_fma_f32 v[64:65], v[52:53], v[100:101], v[66:67] op_sel:[1,0,1] op_sel_hi:[0,1,0] neg_lo:[0,0,1] neg_hi:[0,0,1]
	v_pk_fma_f32 v[52:53], v[52:53], v[100:101], v[66:67] op_sel:[1,0,1] op_sel_hi:[0,1,0]
	v_pk_mul_f32 v[70:71], v[100:101], v[58:59]
	v_pk_mul_f32 v[66:67], v[100:101], v[58:59] op_sel:[1,0] op_sel_hi:[0,1]
	v_pk_fma_f32 v[58:59], v[100:101], v[54:55], v[66:67] neg_lo:[0,0,1] neg_hi:[0,0,1]
	v_pk_fma_f32 v[66:67], v[100:101], v[54:55], v[66:67]
	v_pk_fma_f32 v[68:69], v[100:101], v[54:55], v[70:71] op_sel:[0,1,1] op_sel_hi:[1,0,0] neg_lo:[0,0,1] neg_hi:[0,0,1]
	v_pk_fma_f32 v[54:55], v[100:101], v[54:55], v[70:71] op_sel:[0,1,1] op_sel_hi:[1,0,0]
	v_pk_mul_f32 v[74:75], v[100:101], v[48:49]
	v_pk_mul_f32 v[70:71], v[100:101], v[48:49] op_sel:[1,0] op_sel_hi:[0,1]
	v_pk_fma_f32 v[48:49], v[100:101], v[44:45], v[70:71] neg_lo:[0,0,1] neg_hi:[0,0,1]
	v_pk_fma_f32 v[70:71], v[100:101], v[44:45], v[70:71]
	v_pk_fma_f32 v[72:73], v[100:101], v[44:45], v[74:75] op_sel:[0,1,1] op_sel_hi:[1,0,0] neg_lo:[0,0,1] neg_hi:[0,0,1]
	v_pk_fma_f32 v[44:45], v[100:101], v[44:45], v[74:75] op_sel:[0,1,1] op_sel_hi:[1,0,0]
	v_pk_mul_f32 v[78:79], v[100:101], v[50:51]
	v_pk_mul_f32 v[74:75], v[100:101], v[50:51] op_sel:[1,0] op_sel_hi:[0,1]
	v_pk_fma_f32 v[50:51], v[100:101], v[46:47], v[74:75] neg_lo:[0,0,1] neg_hi:[0,0,1]
	v_pk_fma_f32 v[74:75], v[100:101], v[46:47], v[74:75]
	v_pk_fma_f32 v[76:77], v[100:101], v[46:47], v[78:79] op_sel:[0,1,1] op_sel_hi:[1,0,0] neg_lo:[0,0,1] neg_hi:[0,0,1]
	v_pk_fma_f32 v[46:47], v[100:101], v[46:47], v[78:79] op_sel:[0,1,1] op_sel_hi:[1,0,0]
	v_pk_mul_f32 v[82:83], v[100:101], v[40:41]
	v_pk_mul_f32 v[78:79], v[100:101], v[40:41] op_sel:[1,0] op_sel_hi:[0,1]
	v_pk_fma_f32 v[40:41], v[100:101], v[36:37], v[78:79] neg_lo:[0,0,1] neg_hi:[0,0,1]
	v_pk_fma_f32 v[78:79], v[100:101], v[36:37], v[78:79]
	v_pk_fma_f32 v[80:81], v[100:101], v[36:37], v[82:83] op_sel:[0,1,1] op_sel_hi:[1,0,0] neg_lo:[0,0,1] neg_hi:[0,0,1]
	v_pk_fma_f32 v[36:37], v[100:101], v[36:37], v[82:83] op_sel:[0,1,1] op_sel_hi:[1,0,0]
	v_pk_mul_f32 v[86:87], v[100:101], v[42:43]
	v_pk_mul_f32 v[82:83], v[100:101], v[42:43] op_sel:[1,0] op_sel_hi:[0,1]
	v_pk_mul_f32 v[92:93], v[100:101], v[32:33]
	v_pk_mul_f32 v[32:33], v[100:101], v[32:33] op_sel:[1,0] op_sel_hi:[0,1]
	v_pk_fma_f32 v[42:43], v[100:101], v[38:39], v[82:83] neg_lo:[0,0,1] neg_hi:[0,0,1]
	v_pk_fma_f32 v[82:83], v[100:101], v[38:39], v[82:83]
	v_pk_fma_f32 v[84:85], v[100:101], v[38:39], v[86:87] op_sel:[0,1,1] op_sel_hi:[1,0,0] neg_lo:[0,0,1] neg_hi:[0,0,1]
	v_pk_fma_f32 v[38:39], v[100:101], v[38:39], v[86:87] op_sel:[0,1,1] op_sel_hi:[1,0,0]
	v_pk_fma_f32 v[86:87], v[100:101], v[28:29], v[32:33] neg_lo:[0,0,1] neg_hi:[0,0,1]
	v_pk_fma_f32 v[88:89], v[100:101], v[28:29], v[32:33]
	v_pk_fma_f32 v[90:91], v[100:101], v[28:29], v[92:93] op_sel:[0,1,1] op_sel_hi:[1,0,0] neg_lo:[0,0,1] neg_hi:[0,0,1]
	v_pk_fma_f32 v[92:93], v[100:101], v[28:29], v[92:93] op_sel:[0,1,1] op_sel_hi:[1,0,0]
	v_pk_mul_f32 v[28:29], v[100:101], v[34:35]
	v_pk_mul_f32 v[32:33], v[100:101], v[34:35] op_sel:[1,0] op_sel_hi:[0,1]
	v_pk_fma_f32 v[94:95], v[100:101], v[30:31], v[32:33] neg_lo:[0,0,1] neg_hi:[0,0,1]
	v_pk_fma_f32 v[96:97], v[100:101], v[30:31], v[32:33]
	v_pk_fma_f32 v[98:99], v[100:101], v[30:31], v[28:29] op_sel:[0,1,1] op_sel_hi:[1,0,0] neg_lo:[0,0,1] neg_hi:[0,0,1]
	v_pk_fma_f32 v[100:101], v[100:101], v[30:31], v[28:29] op_sel:[0,1,1] op_sel_hi:[1,0,0]
	v_lshlrev_b32_e32 v28, 1, v105
	v_mov_b32_e32 v29, v0
	v_lshl_add_u64 v[28:29], s[24:25], 0, v[28:29]
	v_lshlrev_b64 v[30:31], 1, v[102:103]
	v_lshl_add_u64 v[102:103], s[24:25], 0, v[30:31]
	v_mul_u32_u24_e32 v3, 0x110, v105
	v_lshlrev_b32_e32 v40, 2, v104
	v_lshl_add_u64 v[104:105], v[28:29], 0, v[30:31]
	s_waitcnt vmcnt(1)
; __device__ __forceinline__ float lo_f(unsigned w) { return __uint_as_float(w << 16); }
; __device__ __forceinline__ float hi_f(unsigned w) { return __uint_as_float(w & 0xffff0000u); }
; __device__ __forceinline__ void s5_item(CPar p, int l, int s, int g, float* wl) {
;     ...
;     { const int r0 = row_of(s, 0); if (lane < 16) { const u32x4* up = (const u32x4*)(U + (size_t)(r0 + lane) * 512 + g * 16); ua = up[0]; ub = up[1]; } }
;     for (int blk = 0; blk < nblk; ++blk) {
;         const int r0 = row_of(s, blk * 16);
;         const u32x4 ca = ua, cbv = ub;
;         if (blk + 1 < nblk && lane < 16) { const int r1 = row_of(s, blk * 16 + 16); const u32x4* up = (const u32x4*)(U + (size_t)(r1 + lane) * 512 + g * 16); ua = up[0]; ub = up[1]; }
; #pragma unroll
;         for (int i = 0; i < 16; ++i) {
;             float br4[4] = {0.f, 0.f, 0.f, 0.f}, bi4[4] = {0.f, 0.f, 0.f, 0.f};
; #pragma unroll
;             for (int w = 0; w < 8; ++w) { const unsigned word = (unsigned)__builtin_amdgcn_readlane((int)(w < 4 ? ca[w] : cbv[w - 4]), i);
;                 const float u0 = lo_f(word), u1 = hi_f(word);
;                 br4[w & 3] += bbr[2 * w] * u0 + bbr[2 * w + 1] * u1; bi4[w & 3] += bbi[2 * w] * u0 + bbi[2 * w + 1] * u1; }
;             const float bur = (br4[0] + br4[1]) + (br4[2] + br4[3]), bui = (bi4[0] + bi4[1]) + (bi4[2] + bi4[3]);
	v_mov_b64_e32 v[30:31], v[22:23]
	s_waitcnt vmcnt(0)
	v_mov_b64_e32 v[34:35], v[26:27]
	v_mov_b32_e32 v63, v57
	v_mov_b32_e32 v53, v65
	v_mov_b32_e32 v67, v59
	v_mov_b32_e32 v55, v69
	v_mov_b32_e32 v71, v49
	v_mov_b32_e32 v45, v73
	v_mov_b32_e32 v75, v51
	v_mov_b32_e32 v47, v77
	v_mov_b32_e32 v79, v41
	v_mov_b32_e32 v37, v81
	v_mov_b32_e32 v83, v43
	v_mov_b32_e32 v39, v85
	v_mov_b32_e32 v89, v87
	v_mov_b32_e32 v93, v91
	v_mov_b32_e32 v97, v95
	v_mov_b32_e32 v101, v99
	v_add3_u32 v1, s52, v3, v1
	v_lshl_add_u32 v42, v108, 1, s52
	v_mov_b32_e32 v3, v2
	v_mov_b32_e32 v61, v60
	v_mov_b64_e32 v[28:29], v[20:21]
	v_mov_b64_e32 v[32:33], v[24:25]
	v_mov_b32_e32 v216, v62
	v_mov_b32_e32 v217, v65
	v_mov_b32_e32 v218, v52
	v_mov_b32_e32 v219, v57
	v_mov_b32_e32 v220, v66
	v_mov_b32_e32 v221, v69
	v_mov_b32_e32 v222, v54
	v_mov_b32_e32 v223, v59
	v_mov_b32_e32 v224, v70
	v_mov_b32_e32 v225, v73
	v_mov_b32_e32 v226, v44
	v_mov_b32_e32 v227, v49
	v_mov_b32_e32 v228, v74
	v_mov_b32_e32 v229, v77
	v_mov_b32_e32 v230, v46
	v_mov_b32_e32 v231, v51
	v_mov_b32_e32 v232, v78
	v_mov_b32_e32 v233, v81
	v_mov_b32_e32 v234, v36
	v_mov_b32_e32 v235, v41
	v_mov_b32_e32 v236, v82
	v_mov_b32_e32 v237, v85
	v_mov_b32_e32 v238, v38
	v_mov_b32_e32 v239, v43
	v_mov_b32_e32 v240, v88
	v_mov_b32_e32 v241, v91
	v_mov_b32_e32 v242, v92
	v_mov_b32_e32 v243, v87
	v_mov_b32_e32 v244, v96
	v_mov_b32_e32 v245, v99
	v_mov_b32_e32 v246, v100
	v_mov_b32_e32 v247, v95
	v_and_b32_e32 v198, 15, v108
	v_lshrrev_b32_e32 v199, 4, v108
	v_mul_u32_u24_e32 v180, 0x90, v108
	v_add_u32_e32 v180, s52, v180
	v_add_u32_e32 v180, 0x1200, v180
	ds_write_b128 v180, v[216:219]
	ds_write_b128 v180, v[220:223] offset:16
	ds_write_b128 v180, v[224:227] offset:32
	ds_write_b128 v180, v[228:231] offset:48
	ds_write_b128 v180, v[232:235] offset:64
	ds_write_b128 v180, v[236:239] offset:80
	ds_write_b128 v180, v[240:243] offset:96
	ds_write_b128 v180, v[244:247] offset:112
	v_mul_u32_u24_e32 v181, 0x90, v198
	v_lshl_add_u32 v181, v199, 5, v181
	v_add_u32_e32 v181, s52, v181
	v_add_u32_e32 v181, 0x1200, v181
	s_waitcnt lgkmcnt(0)
	ds_read_b128 v[216:219], v181
	ds_read_b128 v[220:223], v181 offset:16
	ds_read_b128 v[224:227], v181 offset:2304
	ds_read_b128 v[228:231], v181 offset:2320
	ds_read_b128 v[232:235], v181 offset:4608
	ds_read_b128 v[236:239], v181 offset:4624
	ds_read_b128 v[240:243], v181 offset:6912
	ds_read_b128 v[244:247], v181 offset:6928
	v_lshlrev_b32_e32 v182, 3, v199
	v_mov_b32_e32 v183, 0
	v_lshl_add_u64 v[184:185], v[102:103], 0, v[182:183]
	v_mul_u32_u24_e32 v190, 0x50, v198
	v_lshl_add_u32 v190, v199, 4, v190
	v_add_u32_e32 v190, s52, v190
	v_add_u32_e32 v190, 0x1200, v190
	v_mul_u32_u24_e32 v191, 0x50, v108
	v_add_u32_e32 v191, s52, v191
	v_add_u32_e32 v191, 0x1200, v191
	v_or_b32_e32 v180, s10, v198
	v_mov_b32_e32 v181, 0
	v_lshlrev_b64 v[180:181], 10, v[180:181]
	v_lshl_add_u64 v[180:181], v[184:185], 0, v[180:181]
	global_load_dwordx2 v[186:187], v[180:181], off
	s_waitcnt vmcnt(0) lgkmcnt(0)
	s_branch .LBB0_681
.LBB0_680:
	s_or_b64 exec, exec, s[24:25]
	s_add_i32 s6, s11, -16
	s_cmp_eq_u32 s12, 0
	s_cselect_b32 s13, s10, s6
	v_or_b32_e32 v192, s13, v40
	v_ashrrev_i32_e32 v193, 31, v192
	v_lshlrev_b64 v[192:193], 10, v[192:193]
	v_lshl_add_u64 v[192:193], v[104:105], 0, v[192:193]
	global_load_ushort v194, v[192:193], off
	global_load_ushort v195, v[192:193], off offset:1024
	global_load_ushort v196, v[192:193], off offset:2048
	global_load_ushort v197, v[192:193], off offset:3072
	v_add_u32_e32 v180, s11, v198
	v_mov_b32_e32 v181, 0
	v_lshlrev_b64 v[180:181], 10, v[180:181]
	v_lshl_add_u64 v[180:181], v[184:185], 0, v[180:181]
	global_load_dwordx2 v[188:189], v[180:181], off
	v_lshlrev_b32_e32 v176, 16, v186
	v_and_b32_e32 v177, 0xffff0000, v186
	v_lshlrev_b32_e32 v178, 16, v187
	v_and_b32_e32 v179, 0xffff0000, v187
	v_mfma_f32_16x16x4_f32 v[124:127], v176, v216, 0
	v_mfma_f32_16x16x4_f32 v[128:131], v176, v217, 0
	v_mfma_f32_16x16x4_f32 v[132:135], v176, v224, 0
	v_mfma_f32_16x16x4_f32 v[140:143], v176, v225, 0
	v_mfma_f32_16x16x4_f32 v[144:147], v176, v232, 0
	v_mfma_f32_16x16x4_f32 v[148:151], v176, v233, 0
	v_mfma_f32_16x16x4_f32 v[152:155], v176, v240, 0
	v_mfma_f32_16x16x4_f32 v[248:251], v176, v241, 0
	v_mfma_f32_16x16x4_f32 v[124:127], v177, v218, v[124:127]
	v_mfma_f32_16x16x4_f32 v[128:131], v177, v219, v[128:131]
	v_mfma_f32_16x16x4_f32 v[132:135], v177, v226, v[132:135]
	v_mfma_f32_16x16x4_f32 v[140:143], v177, v227, v[140:143]
	v_mfma_f32_16x16x4_f32 v[144:147], v177, v234, v[144:147]
	v_mfma_f32_16x16x4_f32 v[148:151], v177, v235, v[148:151]
	v_mfma_f32_16x16x4_f32 v[152:155], v177, v242, v[152:155]
	v_mfma_f32_16x16x4_f32 v[248:251], v177, v243, v[248:251]
	v_mfma_f32_16x16x4_f32 v[124:127], v178, v220, v[124:127]
	v_mfma_f32_16x16x4_f32 v[128:131], v178, v221, v[128:131]
	v_mfma_f32_16x16x4_f32 v[132:135], v178, v228, v[132:135]
	v_mfma_f32_16x16x4_f32 v[140:143], v178, v229, v[140:143]
	v_mfma_f32_16x16x4_f32 v[144:147], v178, v236, v[144:147]
	v_mfma_f32_16x16x4_f32 v[148:151], v178, v237, v[148:151]
	v_mfma_f32_16x16x4_f32 v[152:155], v178, v244, v[152:155]
	v_mfma_f32_16x16x4_f32 v[248:251], v178, v245, v[248:251]
	v_mfma_f32_16x16x4_f32 v[124:127], v179, v222, v[124:127]
	v_mfma_f32_16x16x4_f32 v[128:131], v179, v223, v[128:131]
	v_mfma_f32_16x16x4_f32 v[132:135], v179, v230, v[132:135]
	v_mfma_f32_16x16x4_f32 v[140:143], v179, v231, v[140:143]
	v_mfma_f32_16x16x4_f32 v[144:147], v179, v238, v[144:147]
	v_mfma_f32_16x16x4_f32 v[148:151], v179, v239, v[148:151]
	v_mfma_f32_16x16x4_f32 v[152:155], v179, v246, v[152:155]
	v_mfma_f32_16x16x4_f32 v[248:251], v179, v247, v[248:251]
	s_nop 7
	s_nop 1
	ds_write_b128 v190, v[124:127]
	ds_write_b128 v190, v[128:131] offset:5120
	ds_write_b128 v190, v[132:135] offset:1280
	ds_write_b128 v190, v[140:143] offset:6400
	ds_write_b128 v190, v[144:147] offset:2560
	ds_write_b128 v190, v[148:151] offset:7680
	ds_write_b128 v190, v[152:155] offset:3840
	ds_write_b128 v190, v[248:251] offset:8960
	s_waitcnt lgkmcnt(0)
; __device__ __forceinline__ float lo_f(unsigned w) { return __uint_as_float(w << 16); }
; __device__ __forceinline__ float hi_f(unsigned w) { return __uint_as_float(w & 0xffff0000u); }
; __device__ __forceinline__ bf16_t f2bf_(float v) { return (bf16_t)(pk2(v, v) & 0xffffu); }
; __device__ __forceinline__ void s5_item(CPar p, int l, int s, int g, float* wl) {
;     ...
;         for (int i = 0; i < 16; ++i) {
;             float br4[4] = {0.f, 0.f, 0.f, 0.f}, bi4[4] = {0.f, 0.f, 0.f, 0.f};
; #pragma unroll
;             for (int w = 0; w < 8; ++w) { const unsigned word = (unsigned)__builtin_amdgcn_readlane((int)(w < 4 ? ca[w] : cbv[w - 4]), i);
;                 const float u0 = lo_f(word), u1 = hi_f(word);
;                 br4[w & 3] += bbr[2 * w] * u0 + bbr[2 * w + 1] * u1; bi4[w & 3] += bbi[2 * w] * u0 + bbi[2 * w + 1] * u1; }
;             const float bur = (br4[0] + br4[1]) + (br4[2] + br4[3]), bui = (bi4[0] + bi4[1]) + (bi4[2] + bi4[3]);
;             const float nxr = ab_re * xr - ab_im * xi + bur, nxi = ab_re * xi + ab_im * xr + bui; xr = nxr; xi = nxi;
;             Xb[i * LBX + lane] = f2bf_(xr); Xb[i * LBX + 64 + lane] = f2bf_(xi);
	ds_read_b128 v[124:127], v191
	ds_read_b128 v[128:131], v191 offset:16
	ds_read_b128 v[132:135], v191 offset:32
	ds_read_b128 v[140:143], v191 offset:48
	ds_read_b128 v[144:147], v191 offset:5120
	ds_read_b128 v[148:151], v191 offset:5136
	ds_read_b128 v[152:155], v191 offset:5152
	ds_read_b128 v[248:251], v191 offset:5168
	s_waitcnt lgkmcnt(0)
	v_fma_f32 v180, v2, v107, v144
	v_fma_f32 v181, v2, v106, v124
	v_fma_f32 v180, -v60, v106, v180
	v_fma_f32 v106, v60, v107, v181
	v_mov_b32_e32 v107, v180
	v_cvt_pk_bf16_f32 v182, v107, v107
	ds_write_b16 v42, v182
	v_cvt_pk_bf16_f32 v183, v106, v106
	ds_write_b16 v42, v183 offset:128
	v_fma_f32 v180, v2, v107, v145
	v_fma_f32 v181, v2, v106, v125
	v_fma_f32 v180, -v60, v106, v180
	v_fma_f32 v106, v60, v107, v181
	v_mov_b32_e32 v107, v180
	v_cvt_pk_bf16_f32 v182, v107, v107
	ds_write_b16 v42, v182 offset:272
	v_cvt_pk_bf16_f32 v183, v106, v106
	ds_write_b16 v42, v183 offset:400
	v_fma_f32 v180, v2, v107, v146
	v_fma_f32 v181, v2, v106, v126
	v_fma_f32 v180, -v60, v106, v180
	v_fma_f32 v106, v60, v107, v181
	v_mov_b32_e32 v107, v180
	v_cvt_pk_bf16_f32 v182, v107, v107
	ds_write_b16 v42, v182 offset:544
	v_cvt_pk_bf16_f32 v183, v106, v106
	ds_write_b16 v42, v183 offset:672
	v_fma_f32 v180, v2, v107, v147
	v_fma_f32 v181, v2, v106, v127
	v_fma_f32 v180, -v60, v106, v180
	v_fma_f32 v106, v60, v107, v181
	v_mov_b32_e32 v107, v180
	v_cvt_pk_bf16_f32 v182, v107, v107
	ds_write_b16 v42, v182 offset:816
	v_cvt_pk_bf16_f32 v183, v106, v106
	ds_write_b16 v42, v183 offset:944
	v_fma_f32 v180, v2, v107, v148
	v_fma_f32 v181, v2, v106, v128
	v_fma_f32 v180, -v60, v106, v180
	v_fma_f32 v106, v60, v107, v181
	v_mov_b32_e32 v107, v180
	v_cvt_pk_bf16_f32 v182, v107, v107
	ds_write_b16 v42, v182 offset:1088
	v_cvt_pk_bf16_f32 v183, v106, v106
	ds_write_b16 v42, v183 offset:1216
	v_fma_f32 v180, v2, v107, v149
	v_fma_f32 v181, v2, v106, v129
	v_fma_f32 v180, -v60, v106, v180
	v_fma_f32 v106, v60, v107, v181
	v_mov_b32_e32 v107, v180
	v_cvt_pk_bf16_f32 v182, v107, v107
	ds_write_b16 v42, v182 offset:1360
	v_cvt_pk_bf16_f32 v183, v106, v106
	ds_write_b16 v42, v183 offset:1488
	v_fma_f32 v180, v2, v107, v150
	v_fma_f32 v181, v2, v106, v130
	v_fma_f32 v180, -v60, v106, v180
	v_fma_f32 v106, v60, v107, v181
	v_mov_b32_e32 v107, v180
	v_cvt_pk_bf16_f32 v182, v107, v107
	ds_write_b16 v42, v182 offset:1632
	v_cvt_pk_bf16_f32 v183, v106, v106
	ds_write_b16 v42, v183 offset:1760
	v_fma_f32 v180, v2, v107, v151
	v_fma_f32 v181, v2, v106, v131
	v_fma_f32 v180, -v60, v106, v180
	v_fma_f32 v106, v60, v107, v181
	v_mov_b32_e32 v107, v180
	v_cvt_pk_bf16_f32 v182, v107, v107
	ds_write_b16 v42, v182 offset:1904
	v_cvt_pk_bf16_f32 v183, v106, v106
	ds_write_b16 v42, v183 offset:2032
	v_fma_f32 v180, v2, v107, v152
	v_fma_f32 v181, v2, v106, v132
	v_fma_f32 v180, -v60, v106, v180
	v_fma_f32 v106, v60, v107, v181
	v_mov_b32_e32 v107, v180
	v_cvt_pk_bf16_f32 v182, v107, v107
	ds_write_b16 v42, v182 offset:2176
	v_cvt_pk_bf16_f32 v183, v106, v106
	ds_write_b16 v42, v183 offset:2304
	v_fma_f32 v180, v2, v107, v153
	v_fma_f32 v181, v2, v106, v133
	v_fma_f32 v180, -v60, v106, v180
	v_fma_f32 v106, v60, v107, v181
	v_mov_b32_e32 v107, v180
	v_cvt_pk_bf16_f32 v182, v107, v107
	ds_write_b16 v42, v182 offset:2448
	v_cvt_pk_bf16_f32 v183, v106, v106
	ds_write_b16 v42, v183 offset:2576
	v_fma_f32 v180, v2, v107, v154
	v_fma_f32 v181, v2, v106, v134
	v_fma_f32 v180, -v60, v106, v180
	v_fma_f32 v106, v60, v107, v181
	v_mov_b32_e32 v107, v180
	v_cvt_pk_bf16_f32 v182, v107, v107
	ds_write_b16 v42, v182 offset:2720
	v_cvt_pk_bf16_f32 v183, v106, v106
	ds_write_b16 v42, v183 offset:2848
	v_fma_f32 v180, v2, v107, v155
	v_fma_f32 v181, v2, v106, v135
	v_fma_f32 v180, -v60, v106, v180
	v_fma_f32 v106, v60, v107, v181
	v_mov_b32_e32 v107, v180
	v_cvt_pk_bf16_f32 v182, v107, v107
	ds_write_b16 v42, v182 offset:2992
	v_cvt_pk_bf16_f32 v183, v106, v106
	ds_write_b16 v42, v183 offset:3120
	v_fma_f32 v180, v2, v107, v248
	v_fma_f32 v181, v2, v106, v140
	v_fma_f32 v180, -v60, v106, v180
	v_fma_f32 v106, v60, v107, v181
	v_mov_b32_e32 v107, v180
	v_cvt_pk_bf16_f32 v182, v107, v107
	ds_write_b16 v42, v182 offset:3264
	v_cvt_pk_bf16_f32 v183, v106, v106
	ds_write_b16 v42, v183 offset:3392
	v_fma_f32 v180, v2, v107, v249
	v_fma_f32 v181, v2, v106, v141
	v_fma_f32 v180, -v60, v106, v180
	v_fma_f32 v106, v60, v107, v181
	v_mov_b32_e32 v107, v180
	v_cvt_pk_bf16_f32 v182, v107, v107
	ds_write_b16 v42, v182 offset:3536
	v_cvt_pk_bf16_f32 v183, v106, v106
	ds_write_b16 v42, v183 offset:3664
	v_fma_f32 v180, v2, v107, v250
	v_fma_f32 v181, v2, v106, v142
	v_fma_f32 v180, -v60, v106, v180
	v_fma_f32 v106, v60, v107, v181
	v_mov_b32_e32 v107, v180
	v_cvt_pk_bf16_f32 v182, v107, v107
	ds_write_b16 v42, v182 offset:3808
	v_cvt_pk_bf16_f32 v183, v106, v106
	ds_write_b16 v42, v183 offset:3936
	v_fma_f32 v180, v2, v107, v251
	v_fma_f32 v181, v2, v106, v143
	v_fma_f32 v180, -v60, v106, v180
	v_fma_f32 v106, v60, v107, v181
	v_mov_b32_e32 v107, v180
	v_cvt_pk_bf16_f32 v182, v107, v107
	ds_write_b16 v42, v182 offset:4080
	v_cvt_pk_bf16_f32 v183, v106, v106
	ds_write_b16 v42, v183 offset:4208
	s_add_i32 s12, s12, 1
	s_add_i32 s11, s11, 16
	s_cmpk_eq_i32 s12, 0x81
	s_waitcnt lgkmcnt(0)
; __device__ __forceinline__ float bf2f(bf16_t v) { return __uint_as_float((unsigned)v << 16); }
; __device__ __forceinline__ float geluf_(float y) { const float a = 0.7978845608f * (y + 0.044715f * y * y * y); const float t = __expf(2.f * a); return 0.5f * y * (2.f - 2.f * __builtin_amdgcn_rcpf(t + 1.f)); }
; __device__ __forceinline__ bf16_t f2bf_(float v) { return (bf16_t)(pk2(v, v) & 0xffffu); }
; __device__ __forceinline__ void s5_item(CPar p, int l, int s, int g, float* wl) {
;     ...
;         __builtin_amdgcn_wave_barrier(); asm volatile("s_waitcnt lgkmcnt(0)" ::: "memory");
;         f32x4 y = {0.f, 0.f, 0.f, 0.f};
; #pragma unroll
;         for (int ks = 0; ks < 4; ++ks) y = __builtin_amdgcn_mfma_f32_16x16x32_bf16(*(const bf16x8*)(Xb + fr * LBX + ks * 32 + fq * 8), cfrag[ks], y, 0, 0, 0);
; #pragma unroll
;         for (int r = 0; r < 4; ++r) { bf16_t* up = U + (size_t)(r0 + fq * 4 + r) * 512 + g * 16 + fr; *up = f2bf_(geluf_(y[r] + dsk * bf2f(*up))); }
;         __builtin_amdgcn_wave_barrier(); asm volatile("s_waitcnt lgkmcnt(0)" ::: "memory");
	ds_read_b128 v[20:23], v1
	ds_read_b128 v[24:27], v1 offset:64
	s_waitcnt lgkmcnt(1)
	v_mfma_f32_16x16x32_bf16 v[20:23], v[20:23], v[4:7], 0
	s_waitcnt lgkmcnt(0)
	v_mfma_f32_16x16x32_bf16 v[20:23], v[24:27], v[8:11], v[20:23]
	ds_read_b128 v[24:27], v1 offset:128
	ds_read_b128 v[110:113], v1 offset:192
	s_waitcnt lgkmcnt(1)
	v_mfma_f32_16x16x32_bf16 v[20:23], v[24:27], v[12:15], v[20:23]
	v_or_b32_e32 v24, s13, v40
	v_ashrrev_i32_e32 v25, 31, v24
	v_lshlrev_b64 v[26:27], 10, v[24:25]
	v_lshl_add_u64 v[26:27], v[104:105], 0, v[26:27]
	s_waitcnt lgkmcnt(0)
	v_mfma_f32_16x16x32_bf16 v[20:23], v[110:113], v[16:19], v[20:23]
	v_or_b32_e32 v110, 1, v24
	v_ashrrev_i32_e32 v111, 31, v110
	v_lshlrev_b64 v[110:111], 10, v[110:111]
	v_lshl_add_u64 v[110:111], v[104:105], 0, v[110:111]
	s_waitcnt vmcnt(0)
	v_lshlrev_b32_e32 v25, 16, v194
	s_nop 1
	v_fma_f32 v20, v109, v25, v20
	v_mul_f32_e32 v25, 0x3d372713, v20
	v_mul_f32_e32 v25, v20, v25
	v_fma_f32 v25, v20, v25, v20
	v_mul_f32_e32 v25, 0x3f4c422a, v25
	v_add_f32_e32 v25, v25, v25
	v_mul_f32_e32 v25, 0x3fb8aa3b, v25
	v_exp_f32_e32 v25, v25
	v_mul_f32_e32 v20, 0.5, v20
	v_add_f32_e32 v25, 1.0, v25
	v_rcp_f32_e32 v25, v25
	s_nop 0
	v_fma_f32 v25, v25, -2.0, 2.0
	v_mul_f32_e32 v20, v20, v25
	v_cvt_pk_bf16_f32 v20, v20, v20
	v_lshlrev_b32_e32 v25, 16, v195
	v_fma_f32 v21, v109, v25, v21
	v_mul_f32_e32 v25, 0x3d372713, v21
	v_mul_f32_e32 v25, v21, v25
	v_fma_f32 v25, v21, v25, v21
	v_mul_f32_e32 v25, 0x3f4c422a, v25
	v_add_f32_e32 v25, v25, v25
	v_mul_f32_e32 v25, 0x3fb8aa3b, v25
	v_exp_f32_e32 v25, v25
	global_store_short v[26:27], v20, off
	v_mul_f32_e32 v20, 0.5, v21
	v_add_f32_e32 v25, 1.0, v25
	v_rcp_f32_e32 v25, v25
	s_nop 0
	v_fma_f32 v21, v25, -2.0, 2.0
	v_mul_f32_e32 v20, v20, v21
	v_cvt_pk_bf16_f32 v25, v20, v20
	v_or_b32_e32 v20, 2, v24
	v_ashrrev_i32_e32 v21, 31, v20
	v_lshlrev_b64 v[20:21], 10, v[20:21]
	v_lshl_add_u64 v[20:21], v[104:105], 0, v[20:21]
	v_or_b32_e32 v24, 3, v24
	global_store_short v[110:111], v25, off
	v_lshlrev_b32_e32 v26, 16, v196
	v_fma_f32 v22, v109, v26, v22
	v_mul_f32_e32 v26, 0x3d372713, v22
	v_mul_f32_e32 v26, v22, v26
	v_fma_f32 v26, v22, v26, v22
	v_mul_f32_e32 v26, 0x3f4c422a, v26
	v_add_f32_e32 v26, v26, v26
	v_mul_f32_e32 v26, 0x3fb8aa3b, v26
	v_exp_f32_e32 v26, v26
	v_mul_f32_e32 v22, 0.5, v22
	v_add_f32_e32 v26, 1.0, v26
	v_rcp_f32_e32 v26, v26
	s_nop 0
	v_fma_f32 v25, v26, -2.0, 2.0
	v_mul_f32_e32 v22, v22, v25
	v_ashrrev_i32_e32 v25, 31, v24
	v_lshlrev_b64 v[24:25], 10, v[24:25]
	v_lshl_add_u64 v[24:25], v[104:105], 0, v[24:25]
	v_cvt_pk_bf16_f32 v22, v22, v22
	v_lshlrev_b32_e32 v26, 16, v197
	v_fmac_f32_e32 v23, v109, v26
	v_mul_f32_e32 v26, 0x3d372713, v23
	v_mul_f32_e32 v26, v23, v26
	v_fma_f32 v26, v23, v26, v23
	v_mul_f32_e32 v26, 0x3f4c422a, v26
	v_add_f32_e32 v26, v26, v26
	v_mul_f32_e32 v26, 0x3fb8aa3b, v26
	v_exp_f32_e32 v26, v26
	global_store_short v[20:21], v22, off
	v_mul_f32_e32 v20, 0.5, v23
	v_add_f32_e32 v26, 1.0, v26
	v_rcp_f32_e32 v26, v26
	s_nop 0
	v_fma_f32 v21, v26, -2.0, 2.0
	v_mul_f32_e32 v20, v20, v21
	v_cvt_pk_bf16_f32 v20, v20, v20
	global_store_short v[24:25], v20, off
	s_waitcnt lgkmcnt(0)
	v_mov_b64_e32 v[186:187], v[188:189]
	v_mov_b64_e32 v[24:25], v[32:33]
	v_mov_b64_e32 v[20:21], v[28:29]
	v_mov_b64_e32 v[26:27], v[34:35]
	v_mov_b64_e32 v[22:23], v[30:31]
	s_cbranch_scc1 .LBB0_668

; __device__ __forceinline__ unsigned pk2(float lo, float hi) { unsigned r; asm volatile("v_cvt_pk_bf16_f32 %0, %1, %2" : "=v"(r) : "v"(lo), "v"(hi)); return r; }
; __device__ __forceinline__ void attn_item(CPar p, int l, int item, float* wl) {
;     ...
;     for (int d = 0; d < 64; ++d) o[d] = 0.f;
;     const float* kp_new = prompt ? p->out + O_KP + (size_t)(l * 32 + b) * 2064 * 512 + h * 64 : p->out + O_KS + (size_t)(l * 16 + b) * 64 * 512 + h * 64;
;     const float* vp_new = prompt ? p->out + O_VP + (size_t)(l * 32 + b) * 2064 * 512 + h * 64 : p->out + O_VS + (size_t)(l * 16 + b) * 64 * 512 + h * 64;
;     const float* kp_old = p->in[I_CK] + (size_t)(l * 16 + b) * 2048 * 512 + h * 64;
;     const float* vp_old = p->in[I_CV] + (size_t)(l * 16 + b) * 2048 * 512 + h * 64;
;     const int imax = (qt * 64 + 63 < T - 1) ? qt * 64 + 63 : T - 1;
;     const int jtop = nh + imax - 1;
;     float run = 0.f;
;     f32x4 kreg[8], va[4], vb[4];
;     ...
;     if (jtop >= 0) ATT_FETCH(jtop);
;     for (int jt = jtop; jt >= 0; jt -= 32) {
; #pragma unroll
;         for (int e = 0; e < 8; ++e) { const int idx = e * 64 + lane, kr = idx >> 4, pc = idx & 15; u32x2 w; w[0] = pk2(kreg[e][0], kreg[e][1]); w[1] = pk2(kreg[e][2], kreg[e][3]); *(u32x2*)(Kt + kr * 32 + pc * 2) = w; }
; #pragma unroll
;         for (int e = 0; e < 4; ++e) { const int idx = e * 64 + lane, m = idx >> 4, pc = idx & 15;
;             u32x4 w; w[0] = pk2(va[e][0], vb[e][0]); w[1] = pk2(va[e][1], vb[e][1]); w[2] = pk2(va[e][2], vb[e][2]); w[3] = pk2(va[e][3], vb[e][3]); *(u32x4*)(Vp + m * 64 + pc * 4) = w; }
;         __builtin_amdgcn_wave_barrier(); asm volatile("s_waitcnt lgkmcnt(0)" ::: "memory");
;         if (jt - 32 >= 0) ATT_FETCH(jt - 32);
.LBB0_735:
	v_lshlrev_b32_e32 v1, 3, v124
	v_lshlrev_b32_e32 v2, 3, v125
	v_and_b32_e32 v1, 0x78, v1
	v_and_b32_e32 v2, 0x180, v2
	v_add3_u32 v186, s52, v1, v2
	v_lshlrev_b32_e32 v1, 4, v125
	v_and_b32_e32 v1, 0x300, v1
	v_cmp_gt_i32_e64 s[40:41], s8, v126
	v_cmp_le_i32_e64 s[42:43], s8, v126
	v_add_u32_e32 v184, s0, v126
	v_add3_u32 v189, s52, v78, v1
	v_mov_b32_e32 v124, 0
	v_mov_b32_e32 v125, 0
	v_mov_b32_e32 v126, 0
	v_mov_b32_e32 v127, 0
	v_mov_b32_e32 v128, 0
	v_mov_b32_e32 v129, 0
	v_mov_b32_e32 v130, 0
	v_mov_b32_e32 v131, 0
	v_mov_b32_e32 v132, 0
	v_mov_b32_e32 v133, 0
	v_mov_b32_e32 v134, 0
	v_mov_b32_e32 v135, 0
	v_mov_b32_e32 v136, 0
	v_mov_b32_e32 v137, 0
	v_mov_b32_e32 v138, 0
	v_mov_b32_e32 v139, 0
	v_mov_b32_e32 v140, 0
	v_mov_b32_e32 v141, 0
	v_mov_b32_e32 v142, 0
	v_mov_b32_e32 v143, 0
	v_mov_b32_e32 v144, 0
	v_mov_b32_e32 v145, 0
	v_mov_b32_e32 v146, 0
	v_mov_b32_e32 v147, 0
	v_mov_b32_e32 v148, 0
	v_mov_b32_e32 v149, 0
	v_mov_b32_e32 v150, 0
	v_mov_b32_e32 v151, 0
	v_mov_b32_e32 v152, 0
	v_mov_b32_e32 v153, 0
	v_mov_b32_e32 v154, 0
	v_mov_b32_e32 v155, 0
	v_mov_b32_e32 v176, 0
	v_mov_b32_e32 v177, 0
	v_mov_b32_e32 v178, 0
	v_mov_b32_e32 v179, 0
	v_mov_b32_e32 v180, 0
	v_mov_b32_e32 v181, 0
	v_mov_b32_e32 v182, 0
	v_mov_b32_e32 v183, 0
	v_mov_b32_e32 v226, 0
	v_mov_b32_e32 v227, 0
	v_mov_b32_e32 v228, 0
	v_mov_b32_e32 v229, 0
	v_mov_b32_e32 v230, 0
	v_mov_b32_e32 v231, 0
	v_mov_b32_e32 v232, 0
	v_mov_b32_e32 v233, 0
	v_mov_b32_e32 v234, 0
	v_mov_b32_e32 v235, 0
	v_mov_b32_e32 v236, 0
	v_mov_b32_e32 v237, 0
	v_mov_b32_e32 v238, 0
	v_mov_b32_e32 v239, 0
	v_mov_b32_e32 v240, 0
	v_mov_b32_e32 v241, 0
	v_mov_b32_e32 v242, 0
	v_mov_b32_e32 v243, 0
	v_mov_b32_e32 v244, 0
	v_mov_b32_e32 v245, 0
	v_mov_b32_e32 v246, 0
	v_mov_b32_e32 v247, 0
	v_mov_b32_e32 v248, 0
	v_mov_b32_e32 v249, 0
	v_mov_b32_e32 v224, 0
	s_cmp_lt_i32 s1, 0
	s_cbranch_scc1 .LBB0_773
.LBB0_736:
	s_waitcnt vmcnt(0)
	v_cvt_pk_bf16_f32 v2, v4, v5
	v_cvt_pk_bf16_f32 v3, v6, v7
	ds_write_b64 v186, v[2:3]
	s_waitcnt vmcnt(4)
	v_cvt_pk_bf16_f32 v2, v8, v9
	v_cvt_pk_bf16_f32 v3, v10, v11
	ds_write_b64 v186, v[2:3] offset:512
	s_waitcnt vmcnt(3)
	v_cvt_pk_bf16_f32 v2, v12, v13
	v_cvt_pk_bf16_f32 v3, v14, v15
	ds_write_b64 v186, v[2:3] offset:1024
	v_cvt_pk_bf16_f32 v2, v16, v17
	v_cvt_pk_bf16_f32 v3, v18, v19
	ds_write_b64 v186, v[2:3] offset:1536
	v_cvt_pk_bf16_f32 v2, v20, v21
	v_cvt_pk_bf16_f32 v3, v22, v23
	ds_write_b64 v186, v[2:3] offset:2048
	v_cvt_pk_bf16_f32 v2, v24, v25
	v_cvt_pk_bf16_f32 v3, v26, v27
	ds_write_b64 v186, v[2:3] offset:2560
	v_cvt_pk_bf16_f32 v2, v28, v29
	v_cvt_pk_bf16_f32 v3, v30, v31
	ds_write_b64 v186, v[2:3] offset:3072
	v_cvt_pk_bf16_f32 v2, v32, v33
	v_cvt_pk_bf16_f32 v3, v34, v35
	ds_write_b64 v186, v[2:3] offset:3584
	s_waitcnt vmcnt(1)
	v_cvt_pk_bf16_f32 v192, v36, v40
	v_cvt_pk_bf16_f32 v193, v37, v41
	v_cvt_pk_bf16_f32 v194, v38, v42
	v_cvt_pk_bf16_f32 v195, v39, v43
	ds_write_b128 v189, v[192:195] offset:4096
	s_waitcnt vmcnt(0)
	v_cvt_pk_bf16_f32 v192, v44, v48
	v_cvt_pk_bf16_f32 v193, v45, v49
	v_cvt_pk_bf16_f32 v194, v46, v50
	v_cvt_pk_bf16_f32 v195, v47, v51
	ds_write_b128 v189, v[192:195] offset:5120
	v_cvt_pk_bf16_f32 v192, v52, v56
	v_cvt_pk_bf16_f32 v193, v53, v57
	v_cvt_pk_bf16_f32 v194, v54, v58
	v_cvt_pk_bf16_f32 v195, v55, v59
	ds_write_b128 v189, v[192:195] offset:6144
	v_cvt_pk_bf16_f32 v192, v60, v64
	v_cvt_pk_bf16_f32 v193, v61, v65
	v_cvt_pk_bf16_f32 v194, v62, v66
	v_cvt_pk_bf16_f32 v195, v63, v67
	ds_write_b128 v189, v[192:195] offset:7168
	s_waitcnt lgkmcnt(0)
	s_sub_i32 s8, s1, 32
	s_cmp_lt_u32 s1, 32
	s_cbranch_scc1 .LBB0_770
	v_mov_b32_e32 v8, v0
	v_mov_b32_e32 v9, v0
	v_sub_u32_e32 v1, s8, v112
	v_mov_b32_e32 v10, v0
	v_mov_b32_e32 v11, v0
	v_mov_b64_e32 v[4:5], v[8:9]
	v_cmp_lt_i32_e32 vcc, -1, v1
	v_mov_b64_e32 v[6:7], v[10:11]
	s_and_saveexec_b64 s[28:29], vcc
	s_cbranch_execz .LBB0_739
	v_cmp_gt_i32_e32 vcc, s0, v1
	v_mov_b32_e32 v4, s0
	v_mov_b32_e32 v5, v0
	v_cndmask_b32_e64 v4, v4, 0, vcc
	v_sub_u32_e32 v4, v1, v4
	v_cndmask_b32_e32 v3, v71, v75, vcc
	v_cndmask_b32_e32 v2, v70, v74, vcc
	v_lshlrev_b64 v[4:5], 11, v[4:5]
	v_lshl_add_u64 v[2:3], v[2:3], 0, v[4:5]
	v_mov_b32_e32 v79, v0
	v_lshl_add_u64 v[2:3], v[2:3], 0, v[78:79]
	global_load_dwordx4 v[4:7], v[2:3], off

; __device__ __forceinline__ float dot2bf(unsigned a, unsigned b, float c) { return __builtin_amdgcn_fdot2_f32_bf16(__builtin_bit_cast(bf2_t, a), __builtin_bit_cast(bf2_t, b), c, false); }
; __device__ __forceinline__ void attn_item(CPar p, int l, int item, float* wl) {
;     ...
;         const int nk = jt + 1 < 32 ? jt + 1 : 32, npair = (nk + 1) >> 1;
;         for (int m = 0; m < npair; ++m) { const int j0 = jt - 2 * m, j1 = j0 - 1;
;             float z0 = 0.f, z1 = 0.f;
; #pragma unroll
;             for (int d8 = 0; d8 < 8; ++d8) { const u32x4 k0 = *(const u32x4*)(Kt + (2 * m) * 32 + d8 * 4), k1 = *(const u32x4*)(Kt + (2 * m + 1) * 32 + d8 * 4);
; #pragma unroll
;                 for (int c = 0; c < 4; ++c) { z0 = dot2bf(q[d8 * 4 + c], k0[c], z0); z1 = dot2bf(q[d8 * 4 + c], k1[c], z1); } }
.LBB0_770:
	s_min_i32 s6, s1, 31
	s_add_i32 s6, s6, 2
	s_lshr_b32 s6, s6, 1
	s_max_u32 s6, s6, 1
	s_sub_i32 s6, 0, s6
	v_mov_b32_e32 v1, s6
	s_mov_b32 s9, s52
	v_mbcnt_lo_u32_b32 v250, -1, 0
	v_mbcnt_hi_u32_b32 v250, -1, v250
	v_and_b32_e32 v251, 15, v250
	v_lshrrev_b32_e32 v252, 4, v250
	v_lshlrev_b32_e32 v253, 7, v251
	v_lshl_add_u32 v253, v252, 4, v253
	v_add_u32_e32 v253, s52, v253
	v_mul_u32_u24_e32 v251, 0x90, v251
	v_lshl_add_u32 v251, v252, 4, v251
	v_add_u32_e32 v251, s52, v251
	v_add_u32_e32 v251, 0x2000, v251
	ds_read_b128 v[192:195], v253
	ds_read_b128 v[196:199], v253 offset:64
	s_waitcnt lgkmcnt(0)
	v_mfma_f32_16x16x32_bf16 v[216:219], v[192:195], v[80:83], 0
	v_mfma_f32_16x16x32_bf16 v[220:223], v[192:195], v[88:91], 0
	v_mfma_f32_16x16x32_bf16 v[216:219], v[196:199], v[84:87], v[216:219]
	v_mfma_f32_16x16x32_bf16 v[220:223], v[196:199], v[92:95], v[220:223]
	s_nop 7
	s_nop 1
	ds_write_b128 v251, v[216:219]
	ds_write_b128 v251, v[220:223] offset:2304
	s_waitcnt lgkmcnt(0)
	v_mfma_f32_16x16x32_bf16 v[216:219], v[192:195], v[96:99], 0
	v_mfma_f32_16x16x32_bf16 v[220:223], v[192:195], v[104:107], 0
	v_mfma_f32_16x16x32_bf16 v[216:219], v[196:199], v[100:103], v[216:219]
	v_mfma_f32_16x16x32_bf16 v[220:223], v[196:199], v[108:111], v[220:223]
	s_nop 7
	s_nop 1
	ds_write_b128 v251, v[216:219] offset:4608
	ds_write_b128 v251, v[220:223] offset:6912
	s_waitcnt lgkmcnt(0)
	ds_read_b128 v[192:195], v253 offset:2048
	ds_read_b128 v[196:199], v253 offset:2112
	s_waitcnt lgkmcnt(0)
	v_mfma_f32_16x16x32_bf16 v[216:219], v[192:195], v[80:83], 0
	v_mfma_f32_16x16x32_bf16 v[220:223], v[192:195], v[88:91], 0
	v_mfma_f32_16x16x32_bf16 v[216:219], v[196:199], v[84:87], v[216:219]
	v_mfma_f32_16x16x32_bf16 v[220:223], v[196:199], v[92:95], v[220:223]
	s_nop 7
	s_nop 1
	ds_write_b128 v251, v[216:219] offset:64
	ds_write_b128 v251, v[220:223] offset:2368
	s_waitcnt lgkmcnt(0)
	v_mfma_f32_16x16x32_bf16 v[216:219], v[192:195], v[96:99], 0
	v_mfma_f32_16x16x32_bf16 v[220:223], v[192:195], v[104:107], 0
	v_mfma_f32_16x16x32_bf16 v[216:219], v[196:199], v[100:103], v[216:219]
	v_mfma_f32_16x16x32_bf16 v[220:223], v[196:199], v[108:111], v[220:223]
	s_nop 7
	s_nop 1
	ds_write_b128 v251, v[216:219] offset:4672
	ds_write_b128 v251, v[220:223] offset:6976
	s_waitcnt lgkmcnt(0)
	s_waitcnt lgkmcnt(0)
	v_mul_u32_u24_e32 v250, 0x90, v250
	v_add_u32_e32 v250, s52, v250
	v_add_u32_e32 v250, 0x2000, v250
	v_mov_b32_e32 v251, v250
; __device__ __forceinline__ unsigned pk2(float lo, float hi) { unsigned r; asm volatile("v_cvt_pk_bf16_f32 %0, %1, %2" : "=v"(r) : "v"(lo), "v"(hi)); return r; }
; __device__ __forceinline__ float dot2bf(unsigned a, unsigned b, float c) { return __builtin_amdgcn_fdot2_f32_bf16(__builtin_bit_cast(bf2_t, a), __builtin_bit_cast(bf2_t, b), c, false); }
; __device__ __forceinline__ void attn_item(CPar p, int l, int item, float* wl) {
;     ...
;             const bool v0 = active && (j0 < nh + i), v1 = active && (j1 >= 0) && (j1 < nh + i);
;             const float e0 = __expf(-z0), ls0 = -__logf(1.f + e0);
;             const float w0 = v0 ? __expf(ls0 + run) : 0.f; run += v0 ? (ls0 - z0) : 0.f;
;             const float e1 = __expf(-z1), ls1 = -__logf(1.f + e1);
;             const float w1 = v1 ? __expf(ls1 + run) : 0.f; run += v1 ? (ls1 - z1) : 0.f;
;             const unsigned wp = pk2(w0, w1);
; #pragma unroll
;             for (int d4 = 0; d4 < 16; ++d4) { const u32x4 vv = *(const u32x4*)(Vp + m * 64 + d4 * 4);
; #pragma unroll
;                 for (int c = 0; c < 4; ++c) o[d4 * 4 + c] = dot2bf(wp, vv[c], o[d4 * 4 + c]); } }
.LBB0_771:
	ds_read_b64 v[252:253], v250
	v_add_u32_e32 v250, 8, v250
	v_cmp_lt_i32_e32 vcc, s1, v184
	s_and_b64 vcc, s[40:41], vcc
	s_cmp_gt_i32 s1, 0
	s_cselect_b64 s[6:7], -1, 0
	s_and_b64 s[6:7], s[40:41], s[6:7]
	v_cmp_le_i32_e64 s[44:45], s1, v184
	s_addk_i32 s9, 0x100
	s_add_i32 s1, s1, -2
	s_waitcnt lgkmcnt(0)
	v_mov_b32_e32 v3, v252
	v_mov_b32_e32 v79, v253
	s_and_b64 s[44:45], s[6:7], s[44:45]
	v_mul_f32_e32 v212, 0xbfb8aa3b, v3
	v_exp_f32_e32 v212, v212
	s_nop 0
	v_add_f32_e32 v212, 1.0, v212
	v_cmp_gt_f32_e64 s[46:47], s38, v212
	s_nop 1
	v_cndmask_b32_e64 v213, 0, 32, s[46:47]
	v_ldexp_f32 v212, v212, v213
	v_log_f32_e32 v212, v212
	s_nop 0
	v_mul_f32_e32 v213, 0x3f317217, v212
	v_fma_f32 v213, v212, s90, -v213
	v_fmac_f32_e32 v213, 0x3377d1cf, v212
	v_fmac_f32_e32 v213, 0x3f317217, v212
	v_cmp_lt_f32_e64 s[48:49], |v212|, s23
	s_nop 1
	v_cndmask_b32_e64 v212, v212, v213, s[48:49]
	v_cndmask_b32_e64 v213, 0, v211, s[46:47]
	v_sub_f32_e32 v212, v212, v213
	v_sub_f32_e32 v213, v224, v212
	v_sub_f32_e64 v3, -v212, v3
	v_mul_f32_e32 v212, 0xbfb8aa3b, v79
	v_mul_f32_e32 v213, 0x3fb8aa3b, v213
	v_exp_f32_e32 v212, v212
	v_exp_f32_e32 v213, v213
	v_cndmask_b32_e32 v3, 0, v3, vcc
	v_add_f32_e32 v3, v224, v3
	v_add_f32_e32 v212, 1.0, v212
	v_cndmask_b32_e32 v213, 0, v213, vcc
	v_cmp_gt_f32_e32 vcc, s38, v212
	s_nop 1
	v_cndmask_b32_e64 v224, 0, 32, vcc
	v_ldexp_f32 v212, v212, v224
	v_log_f32_e32 v212, v212
	s_nop 0
	v_mul_f32_e32 v224, 0x3f317217, v212
	v_fma_f32 v224, v212, s90, -v224
	v_fmac_f32_e32 v224, 0x3377d1cf, v212
	v_fmac_f32_e32 v224, 0x3f317217, v212
	v_cmp_lt_f32_e64 s[46:47], |v212|, s23
	s_nop 1
	v_cndmask_b32_e64 v212, v212, v224, s[46:47]
	v_cndmask_b32_e32 v224, 0, v211, vcc
	v_sub_f32_e32 v212, v212, v224
	v_sub_f32_e32 v224, v3, v212
	v_mul_f32_e32 v224, 0x3fb8aa3b, v224
	v_exp_f32_e32 v224, v224
	v_sub_f32_e64 v79, -v212, v79
	v_cndmask_b32_e64 v79, 0, v79, s[44:45]
	v_add_co_u32_e32 v1, vcc, 1, v1
	v_cndmask_b32_e64 v224, 0, v224, s[44:45]
	v_cvt_pk_bf16_f32 v212, v213, v224
	s_and_b64 vcc, exec, vcc
	ds_write_b32 v251, v212
	v_add_u32_e32 v251, 4, v251
	v_add_f32_e32 v224, v3, v79
	s_cbranch_vccz .LBB0_771
	s_mov_b32 s1, 0xc2480000
	v_cmp_gt_f32_e32 vcc, s1, v224
	s_or_b64 s[6:7], s[42:43], vcc
	s_waitcnt lgkmcnt(0)
	v_mbcnt_lo_u32_b32 v250, -1, 0
	v_mbcnt_hi_u32_b32 v250, -1, v250
	v_and_b32_e32 v251, 15, v250
	v_lshrrev_b32_e32 v252, 4, v250
	v_lshlrev_b32_e32 v253, 2, v251
	v_lshl_add_u32 v253, v252, 10, v253
	v_add_u32_e32 v253, s52, v253
	v_add_u32_e32 v253, 0x1000, v253
	v_mul_u32_u24_e32 v251, 0x90, v251
	v_lshl_add_u32 v251, v252, 4, v251
	v_add_u32_e32 v251, s52, v251
	v_add_u32_e32 v251, 0x2000, v251
	ds_read_b128 v[216:219], v251
	ds_read_b128 v[220:223], v251 offset:2304
	ds_read_b32 v192, v253
	ds_read_b32 v193, v253 offset:256
	ds_read_b32 v194, v253 offset:512
	ds_read_b32 v195, v253 offset:768
	ds_read_b32 v196, v253 offset:64
	ds_read_b32 v197, v253 offset:320
	ds_read_b32 v198, v253 offset:576
	ds_read_b32 v199, v253 offset:832
	s_waitcnt lgkmcnt(0)
	v_mfma_f32_16x16x32_bf16 v[124:127], v[192:195], v[216:219], v[124:127]
	v_mfma_f32_16x16x32_bf16 v[140:143], v[192:195], v[220:223], v[140:143]
	v_mfma_f32_16x16x32_bf16 v[128:131], v[196:199], v[216:219], v[128:131]
	v_mfma_f32_16x16x32_bf16 v[144:147], v[196:199], v[220:223], v[144:147]
	s_nop 3
	ds_read_b32 v192, v253 offset:128
	ds_read_b32 v193, v253 offset:384
	ds_read_b32 v194, v253 offset:640
	ds_read_b32 v195, v253 offset:896
	ds_read_b32 v196, v253 offset:192
	ds_read_b32 v197, v253 offset:448
	ds_read_b32 v198, v253 offset:704
	ds_read_b32 v199, v253 offset:960
	s_waitcnt lgkmcnt(0)
	v_mfma_f32_16x16x32_bf16 v[132:135], v[192:195], v[216:219], v[132:135]
	v_mfma_f32_16x16x32_bf16 v[148:151], v[192:195], v[220:223], v[148:151]
	v_mfma_f32_16x16x32_bf16 v[136:139], v[196:199], v[216:219], v[136:139]
	v_mfma_f32_16x16x32_bf16 v[152:155], v[196:199], v[220:223], v[152:155]
	s_nop 3
	ds_read_b128 v[216:219], v251 offset:4608
	ds_read_b128 v[220:223], v251 offset:6912
	ds_read_b32 v192, v253
	ds_read_b32 v193, v253 offset:256
	ds_read_b32 v194, v253 offset:512
	ds_read_b32 v195, v253 offset:768
	ds_read_b32 v196, v253 offset:64
	ds_read_b32 v197, v253 offset:320
	ds_read_b32 v198, v253 offset:576
	ds_read_b32 v199, v253 offset:832
	s_waitcnt lgkmcnt(0)
	v_mfma_f32_16x16x32_bf16 v[176:179], v[192:195], v[216:219], v[176:179]
	v_mfma_f32_16x16x32_bf16 v[234:237], v[192:195], v[220:223], v[234:237]
	v_mfma_f32_16x16x32_bf16 v[180:183], v[196:199], v[216:219], v[180:183]
	v_mfma_f32_16x16x32_bf16 v[238:241], v[196:199], v[220:223], v[238:241]
	s_nop 3
	ds_read_b32 v192, v253 offset:128
	ds_read_b32 v193, v253 offset:384
	ds_read_b32 v194, v253 offset:640
	ds_read_b32 v195, v253 offset:896
	ds_read_b32 v196, v253 offset:192
	ds_read_b32 v197, v253 offset:448
	ds_read_b32 v198, v253 offset:704
	ds_read_b32 v199, v253 offset:960
	s_waitcnt lgkmcnt(0)
	v_mfma_f32_16x16x32_bf16 v[226:229], v[192:195], v[216:219], v[226:229]
	v_mfma_f32_16x16x32_bf16 v[242:245], v[192:195], v[220:223], v[242:245]
	v_mfma_f32_16x16x32_bf16 v[230:233], v[196:199], v[216:219], v[230:233]
	v_mfma_f32_16x16x32_bf16 v[246:249], v[196:199], v[220:223], v[246:249]
	s_nop 3
	v_cndmask_b32_e64 v1, 0, 1, s[6:7]
	v_cmp_ne_u32_e32 vcc, 0, v1
	s_cmp_eq_u64 vcc, exec
	s_cselect_b64 s[28:29], -1, 0
	s_and_b64 vcc, exec, s[28:29]
	s_cbranch_vccz .LBB0_774
	s_branch .LBB0_775

; __device__ __forceinline__ unsigned pk2(float lo, float hi) { unsigned r; asm volatile("v_cvt_pk_bf16_f32 %0, %1, %2" : "=v"(r) : "v"(lo), "v"(hi)); return r; }
; __device__ __forceinline__ void attn_item(CPar p, int l, int item, float* wl) {
;     ...
;     if (active) { u32x4* op = (u32x4*)(Q + (size_t)row * 512 + h * 64);
; #pragma unroll
;         for (int e = 0; e < 8; ++e) { u32x4 w; w[0] = pk2(o[e * 8], o[e * 8 + 1]); w[1] = pk2(o[e * 8 + 2], o[e * 8 + 3]); w[2] = pk2(o[e * 8 + 4], o[e * 8 + 5]); w[3] = pk2(o[e * 8 + 6], o[e * 8 + 7]); op[e] = w; } }
.LBB0_775:
	s_nop 7
	s_nop 1
	v_mbcnt_lo_u32_b32 v250, -1, 0
	v_mbcnt_hi_u32_b32 v250, -1, v250
	v_and_b32_e32 v251, 15, v250
	v_lshrrev_b32_e32 v252, 4, v250
	v_mul_u32_u24_e32 v251, 0x90, v251
	v_lshl_add_u32 v251, v252, 3, v251
	v_add_u32_e32 v251, s52, v251
	v_add_u32_e32 v251, 0x2000, v251
	v_cvt_pk_bf16_f32 v192, v124, v125
	v_cvt_pk_bf16_f32 v193, v126, v127
	ds_write_b64 v251, v[192:193]
	v_cvt_pk_bf16_f32 v194, v128, v129
	v_cvt_pk_bf16_f32 v195, v130, v131
	ds_write_b64 v251, v[194:195] offset:32
	v_cvt_pk_bf16_f32 v196, v132, v133
	v_cvt_pk_bf16_f32 v197, v134, v135
	ds_write_b64 v251, v[196:197] offset:64
	v_cvt_pk_bf16_f32 v198, v136, v137
	v_cvt_pk_bf16_f32 v199, v138, v139
	ds_write_b64 v251, v[198:199] offset:96
	v_cvt_pk_bf16_f32 v216, v140, v141
	v_cvt_pk_bf16_f32 v217, v142, v143
	ds_write_b64 v251, v[216:217] offset:2304
	v_cvt_pk_bf16_f32 v218, v144, v145
	v_cvt_pk_bf16_f32 v219, v146, v147
	ds_write_b64 v251, v[218:219] offset:2336
	v_cvt_pk_bf16_f32 v220, v148, v149
	v_cvt_pk_bf16_f32 v221, v150, v151
	ds_write_b64 v251, v[220:221] offset:2368
	v_cvt_pk_bf16_f32 v222, v152, v153
	v_cvt_pk_bf16_f32 v223, v154, v155
	ds_write_b64 v251, v[222:223] offset:2400
	v_cvt_pk_bf16_f32 v192, v176, v177
	v_cvt_pk_bf16_f32 v193, v178, v179
	ds_write_b64 v251, v[192:193] offset:4608
	v_cvt_pk_bf16_f32 v194, v180, v181
	v_cvt_pk_bf16_f32 v195, v182, v183
	ds_write_b64 v251, v[194:195] offset:4640
	v_cvt_pk_bf16_f32 v196, v226, v227
	v_cvt_pk_bf16_f32 v197, v228, v229
	ds_write_b64 v251, v[196:197] offset:4672
	v_cvt_pk_bf16_f32 v198, v230, v231
	v_cvt_pk_bf16_f32 v199, v232, v233
	ds_write_b64 v251, v[198:199] offset:4704
	v_cvt_pk_bf16_f32 v216, v234, v235
	v_cvt_pk_bf16_f32 v217, v236, v237
	ds_write_b64 v251, v[216:217] offset:6912
	v_cvt_pk_bf16_f32 v218, v238, v239
	v_cvt_pk_bf16_f32 v219, v240, v241
	ds_write_b64 v251, v[218:219] offset:6944
	v_cvt_pk_bf16_f32 v220, v242, v243
	v_cvt_pk_bf16_f32 v221, v244, v245
	ds_write_b64 v251, v[220:221] offset:6976
	v_cvt_pk_bf16_f32 v222, v246, v247
	v_cvt_pk_bf16_f32 v223, v248, v249
	ds_write_b64 v251, v[222:223] offset:7008
	s_waitcnt lgkmcnt(0)
	v_mul_u32_u24_e32 v250, 0x90, v250
	v_add_u32_e32 v250, s52, v250
	v_add_u32_e32 v250, 0x2000, v250
	ds_read_b128 v[124:127], v250
	ds_read_b128 v[128:131], v250 offset:16
	ds_read_b128 v[132:135], v250 offset:32
	ds_read_b128 v[136:139], v250 offset:48
	ds_read_b128 v[140:143], v250 offset:64
	ds_read_b128 v[144:147], v250 offset:80
	ds_read_b128 v[148:151], v250 offset:96
	ds_read_b128 v[152:155], v250 offset:112
	s_waitcnt lgkmcnt(0)
	s_and_saveexec_b64 s[0:1], s[40:41]
	s_xor_b64 s[28:29], exec, s[0:1]
	s_cbranch_execz .LBB0_684
	s_waitcnt vmcnt(0)
	global_store_dwordx4 v[68:69], v[124:127], off
	s_nop 1
	global_store_dwordx4 v[68:69], v[128:131], off offset:16
	s_nop 1
	global_store_dwordx4 v[68:69], v[132:135], off offset:32
	s_nop 1
	global_store_dwordx4 v[68:69], v[136:139], off offset:48
	s_nop 1
	global_store_dwordx4 v[68:69], v[140:143], off offset:64
	s_nop 1
	global_store_dwordx4 v[68:69], v[144:147], off offset:80
	s_nop 1
	global_store_dwordx4 v[68:69], v[148:151], off offset:96
	s_nop 1
	global_store_dwordx4 v[68:69], v[152:155], off offset:112
	s_branch .LBB0_684
